# v46: output-projection epilogue issues its gain + residual loads (and their address arithmetic) before the first row-sum exchange wait instead of after it
# speedup vs baseline: 1.0134x; 1.0085x over previous
.LBB0_633:
	s_or_b64 exec, exec, s[0:1]
	s_lshl_b32 s34, s10, 6
	s_cmp_lt_u32 s2, 64
	s_cselect_b64 s[0:1], -1, 0
	s_add_i32 s3, s3, s38
	s_lshl_b32 s11, s36, 5
	v_or_b32_e32 v168, s3, v3
	s_lshl_b32 s3, s18, 8
	s_or_b32 s3, s3, s11
	s_ashr_i32 s11, s10, 31
	s_lshl_b64 s[10:11], s[10:11], 12
	s_add_u32 s10, s12, s10
	s_addc_u32 s11, s13, s11
	s_add_u32 s24, s16, 0x5000000
	v_lshrrev_b32_e32 v227, 4, v132
	s_addc_u32 s25, s17, 0
	s_and_b32 s2, s2, 0xffffff00
	v_lshl_or_b32 v176, v227, 3, s3
	s_add_i32 s2, s2, 16
	v_lshl_add_u32 v0, v3, 2, s2
	v_ashrrev_i32_e32 v177, 31, v176
	v_ashrrev_i32_e32 v169, 31, v168
	v_or_b32_e32 v172, 16, v168
	v_add_u32_e32 v228, 0x1000, v0
	v_lshl_add_u64 v[140:141], v[176:177], 1, s[24:25]
	v_lshlrev_b64 v[0:1], 11, v[168:169]
	v_ashrrev_i32_e32 v173, 31, v172
	v_or_b32_e32 v170, 32, v168
	v_lshl_add_u64 v[180:181], v[140:141], 0, v[0:1]
	v_lshlrev_b64 v[0:1], 11, v[172:173]
	v_ashrrev_i32_e32 v171, 31, v170
	v_lshl_add_u64 v[182:183], v[140:141], 0, v[0:1]
	v_lshlrev_b64 v[0:1], 11, v[170:171]
	v_lshl_add_u64 v[184:185], v[140:141], 0, v[0:1]
	v_or_b32_e32 v0, 48, v168
	v_ashrrev_i32_e32 v1, 31, v0
	v_add_u32_e32 v212, 0x80, v168
	v_lshlrev_b64 v[142:143], 11, v[0:1]
	v_ashrrev_i32_e32 v213, 31, v212
	v_add_u32_e32 v210, 0x90, v168
	v_lshl_add_u64 v[186:187], v[140:141], 0, v[142:143]
	v_lshlrev_b64 v[142:143], 11, v[212:213]
	v_ashrrev_i32_e32 v211, 31, v210
	v_add_u32_e32 v206, 0xa0, v168
	v_lshl_add_u64 v[178:179], v[176:177], 2, s[10:11]
	v_lshl_add_u64 v[190:191], v[140:141], 0, v[142:143]
	v_lshlrev_b64 v[142:143], 11, v[210:211]
	v_ashrrev_i32_e32 v207, 31, v206
	v_add_u32_e32 v204, 0xb0, v168
	global_load_dwordx4 v[132:135], v[178:179], off offset:16
	global_load_dwordx4 v[136:139], v[178:179], off
	global_load_dwordx4 v[216:219], v[180:181], off
	global_load_dwordx4 v[164:167], v[182:183], off
	v_lshl_add_u64 v[192:193], v[140:141], 0, v[142:143]
	v_lshlrev_b64 v[142:143], 11, v[206:207]
	v_ashrrev_i32_e32 v205, 31, v204
	v_lshl_add_u64 v[194:195], v[140:141], 0, v[142:143]
	v_lshlrev_b64 v[142:143], 11, v[204:205]
	global_load_dwordx4 v[160:163], v[184:185], off
	global_load_dwordx4 v[156:159], v[186:187], off
	global_load_dwordx4 v[152:155], v[190:191], off
	global_load_dwordx4 v[148:151], v[192:193], off
	v_lshl_add_u64 v[196:197], v[140:141], 0, v[142:143]
	global_load_dwordx4 v[144:147], v[194:195], off
	global_load_dwordx4 v[140:143], v[196:197], off
	s_andn2_b64 vcc, exec, s[0:1]
	s_cbranch_vccnz .LBB0_639
	s_lshl_b32 s22, s28, 6
	s_ashr_i32 s23, s22, 31
	s_or_b32 s11, s34, 32
	s_lshl_b64 s[22:23], s[22:23], 2
	s_add_u32 s22, s29, s22
	s_addc_u32 s23, s30, s23
	v_mov_b32_e32 v202, 0x100000
	s_branch .LBB0_636
.LBB0_635:
	s_sleep 2
.LBB0_636:
	global_load_dword v203, v2, s[22:23] sc1
	v_subrev_co_u32_e32 v202, vcc, 1, v202
	s_waitcnt vmcnt(0)
	v_readfirstlane_b32 s19, v203
	s_cmp_ge_u32 s19, s11
	s_cbranch_scc1 .LBB0_639
	s_cbranch_vccz .LBB0_635
.LBB0_639:
	s_waitcnt vmcnt(0) lgkmcnt(0)
	s_barrier
	s_and_saveexec_b64 s[22:23], s[4:5]
	s_cbranch_execz .LBB0_641
	s_mov_b64 s[10:11], 0x9000000
	v_lshl_add_u64 v[188:189], v[174:175], 0, s[10:11]
	global_load_dword v208, v[188:189], off sc1
	global_load_dword v209, v[188:189], off offset:4 sc1
	global_load_dword v214, v[188:189], off offset:8 sc1
	global_load_dword v215, v[188:189], off offset:12 sc1
	v_lshl_add_u32 v202, v226, 2, 16
	s_waitcnt vmcnt(3)
	v_add_f32_e32 v208, 0, v208
	s_waitcnt vmcnt(2)
	v_add_f32_e32 v208, v208, v209
	s_waitcnt vmcnt(1)
	v_add_f32_e32 v208, v208, v214
	s_waitcnt vmcnt(0)
	v_add_f32_e32 v208, v208, v215
	ds_write_b32 v202, v208 offset:4096
.LBB0_641:
	s_or_b64 exec, exec, s[22:23]
	s_waitcnt vmcnt(0) lgkmcnt(0)
	s_barrier
	ds_read2_b32 v[188:189], v228 offset1:16
	ds_read2_b32 v[214:215], v228 offset0:32 offset1:48
	ds_read2_b32 v[208:209], v228 offset0:128 offset1:144
	ds_read2_b32 v[202:203], v228 offset0:160 offset1:176
	s_waitcnt lgkmcnt(0)
	s_barrier
	s_waitcnt lgkmcnt(0)
	v_fmamk_f32 v188, v188, 0x3a800000, v222
	v_mul_f32_e32 v198, 0x4f800000, v188
	v_cmp_gt_f32_e32 vcc, s73, v188
	s_cmp_eq_u64 s[20:21], 0
	s_cselect_b64 s[22:23], -1, 0
	v_cndmask_b32_e32 v188, v188, v198, vcc
	v_sqrt_f32_e32 v198, v188
	s_cmp_lg_u64 s[20:21], 0
	s_cselect_b64 s[12:13], -1, 0
	v_add_u32_e32 v199, -1, v198
	v_fma_f32 v200, -v199, v198, v188
	v_cmp_ge_f32_e64 s[10:11], 0, v200
	v_add_u32_e32 v200, 1, v198
	s_nop 0
	v_cndmask_b32_e64 v199, v198, v199, s[10:11]
	v_fma_f32 v198, -v200, v198, v188
	v_cmp_lt_f32_e64 s[10:11], 0, v198
	s_nop 1
	v_cndmask_b32_e64 v198, v199, v200, s[10:11]
	v_mul_f32_e32 v199, 0x37800000, v198
	v_cndmask_b32_e32 v198, v198, v199, vcc
	v_cmp_class_f32_e32 vcc, v188, v247
	s_mov_b64 s[10:11], -1
	s_nop 0
	v_cndmask_b32_e32 v188, v198, v188, vcc
	v_div_scale_f32 v198, s[2:3], v188, v188, 1.0
	v_rcp_f32_e32 v199, v198
	s_nop 0
	v_fma_f32 v200, -v198, v199, 1.0
	v_fmac_f32_e32 v199, v200, v199
	v_div_scale_f32 v200, vcc, 1.0, v188, 1.0
	v_mul_f32_e32 v201, v200, v199
	v_fma_f32 v220, -v198, v201, v200
	v_fmac_f32_e32 v201, v220, v199
	v_fma_f32 v198, -v198, v201, v200
	v_div_fmas_f32 v198, v198, v199, v201
	v_div_fixup_f32 v188, v198, v188, 1.0
	v_pk_mul_f32 v[128:129], v[128:129], v[188:189] op_sel_hi:[1,0]
	v_pk_mul_f32 v[130:131], v[130:131], v[188:189] op_sel_hi:[1,0]
	v_lshlrev_b64 v[200:201], 10, v[168:169]
	v_pk_mul_f32 v[124:125], v[124:125], v[188:189] op_sel_hi:[1,0]
	v_pk_mul_f32 v[126:127], v[126:127], v[188:189] op_sel_hi:[1,0]
	s_and_b64 vcc, exec, s[22:23]
	s_waitcnt vmcnt(0)
	v_lshlrev_b32_e32 v198, 16, v216
	v_and_b32_e32 v199, 0xffff0000, v216
	v_lshlrev_b32_e32 v216, 16, v217
	v_and_b32_e32 v217, 0xffff0000, v217
	v_pk_fma_f32 v[130:131], v[130:131], v[138:139], v[216:217]
	v_pk_fma_f32 v[128:129], v[128:129], v[136:137], v[198:199]
	v_lshlrev_b32_e32 v198, 16, v218
	v_and_b32_e32 v199, 0xffff0000, v218
	v_lshlrev_b32_e32 v216, 16, v219
	v_and_b32_e32 v217, 0xffff0000, v219
	v_pk_fma_f32 v[126:127], v[126:127], v[134:135], v[216:217]
	v_pk_fma_f32 v[124:125], v[124:125], v[132:133], v[198:199]
	v_lshl_add_u64 v[198:199], v[200:201], 2, s[20:21]
	s_cbranch_vccnz .LBB0_643
	v_lshl_add_u64 v[216:217], v[176:177], 2, v[198:199]
	s_mov_b64 s[10:11], 0
	global_store_dwordx4 v[216:217], v[128:131], off
	global_store_dwordx4 v[216:217], v[124:127], off offset:16
